# differential-attention unit epilogue: the 16 gain-vector loads issued together up front; store ladder no longer waits per step
# speedup vs baseline: 1.0142x; 1.0023x over previous
; template <int VAR> __device__ __forceinline__ void attn_unit_a(LAS unsigned char* lds, KP p, int l, int bh, int qb, int wv) {
;     ...
;     const float inv1 = lam / lsum;
;     float ss = 0.f;
; #pragma unroll
;     for (int t = 0; t < 4; ++t)
; #pragma unroll
;         for (int i = 0; i < 8; ++i) { const unsigned ow = o0[(t * 8 + i) * 64]; const float a = __uint_as_float(ow << 16) - O[t][2 * i] * inv1, c = __uint_as_float(ow & 0xffff0000u) - O[t][2 * i + 1] * inv1;
.LBB0_822:
	v_exp_f32_e32 v128, v80
	v_exp_f32_e32 v129, v81
	v_exp_f32_e32 v134, v82
	v_exp_f32_e32 v135, v83
	v_exp_f32_e32 v84, v84
	v_exp_f32_e32 v85, v85
	v_exp_f32_e32 v86, v86
	v_exp_f32_e32 v87, v87
	v_exp_f32_e32 v130, v64
	v_exp_f32_e32 v131, v65
	v_exp_f32_e32 v136, v66
	v_exp_f32_e32 v137, v67
	v_cvt_pk_bf16_f32 v64, v128, v129
	v_cvt_pk_bf16_f32 v65, v134, v135
	v_cvt_pk_bf16_f32 v66, v84, v85
	v_cvt_pk_bf16_f32 v67, v86, v87
	s_waitcnt lgkmcnt(0)
	v_exp_f32_e32 v88, v88
	v_exp_f32_e32 v89, v89
	v_mfma_f32_32x32x16_bf16 v[0:15], v[124:127], v[64:67], v[0:15]
	v_exp_f32_e32 v142, v90
	v_exp_f32_e32 v143, v91
	v_exp_f32_e32 v144, v92
	v_exp_f32_e32 v145, v93
	v_exp_f32_e32 v124, v94
	v_exp_f32_e32 v125, v95
	v_exp_f32_e32 v138, v70
	v_mfma_f32_32x32x16_bf16 v[48:63], v[108:111], v[64:67], v[48:63]
	v_exp_f32_e32 v139, v71
	v_exp_f32_e32 v140, v72
	v_exp_f32_e32 v141, v73
	v_cvt_pk_bf16_f32 v70, v88, v89
	v_cvt_pk_bf16_f32 v71, v142, v143
	v_cvt_pk_bf16_f32 v72, v144, v145
	v_cvt_pk_bf16_f32 v73, v124, v125
	v_exp_f32_e32 v68, v68
	v_exp_f32_e32 v69, v69
	v_mfma_f32_32x32x16_bf16 v[0:15], v[120:123], v[70:73], v[0:15]
	v_cvt_pk_bf16_f32 v80, v130, v131
	v_cvt_pk_bf16_f32 v81, v136, v137
	v_cvt_pk_bf16_f32 v82, v68, v69
	v_cvt_pk_bf16_f32 v83, v138, v139
	v_add_f32_e64 v90, v128, 0
	v_add_f32_e64 v91, v129, 0
	v_exp_f32_e32 v120, v74
	v_pk_add_f32 v[90:91], v[130:131], v[90:91]
	v_mfma_f32_32x32x16_bf16 v[48:63], v[104:107], v[70:73], v[48:63]
	v_add_f32_e64 v90, v134, v90
	v_add_f32_e64 v91, v135, v91
	v_exp_f32_e32 v121, v75
	v_exp_f32_e32 v122, v76
	v_exp_f32_e32 v123, v77
	v_exp_f32_e32 v78, v78
	v_exp_f32_e32 v79, v79
	v_pk_add_f32 v[90:91], v[136:137], v[90:91]
	v_mfma_f32_32x32x16_bf16 v[0:15], v[116:119], v[80:83], v[0:15]
	v_add_f32_e64 v84, v84, v90
	v_add_f32_e64 v85, v85, v91
	v_cvt_pk_bf16_f32 v74, v140, v141
	v_add_f32_e64 v68, v68, v84
	v_add_f32_e64 v69, v69, v85
	v_cvt_pk_bf16_f32 v75, v120, v121
	v_pk_add_f32 v[68:69], v[86:87], v[68:69]
	v_cvt_pk_bf16_f32 v76, v122, v123
	v_cvt_pk_bf16_f32 v77, v78, v79
	v_mfma_f32_32x32x16_bf16 v[48:63], v[100:103], v[80:83], v[48:63]
	v_add_f32_e64 v68, v138, v68
	v_add_f32_e64 v69, v139, v69
	v_add_u32_e32 v116, 0x2200, v132
	v_add_f32_e64 v68, v88, v68
	v_add_f32_e64 v69, v89, v69
	v_readlane_b32 s2, v255, 45
	v_pk_add_f32 v[68:69], v[140:141], v[68:69]
	v_readlane_b32 s3, v255, 46
	v_pk_add_f32 v[68:69], v[142:143], v[68:69]
	v_mfma_f32_32x32x16_bf16 v[0:15], v[112:115], v[74:77], v[0:15]
	v_add_f32_e64 v68, v120, v68
	v_add_f32_e64 v69, v121, v69
	s_lshl_b32 s76, s17, 8
	v_add_f32_e64 v68, v144, v68
	v_add_f32_e64 v69, v145, v69
	s_lshl_b64 s[2:3], s[2:3], 2
	v_pk_add_f32 v[68:69], v[122:123], v[68:69]
	s_nop 0
	v_pk_add_f32 v[68:69], v[124:125], v[68:69]
	v_mfma_f32_32x32x16_bf16 v[48:63], v[96:99], v[74:77], v[48:63]
	ds_read_b64 v[112:113], v116
	ds_read_b64 v[114:115], v116 offset:16
	ds_read_b64 v[108:109], v116 offset:32
	ds_read_b64 v[110:111], v116 offset:48
	ds_read_b64 v[104:105], v116 offset:64
	ds_read_b64 v[106:107], v116 offset:80
	ds_read_b64 v[100:101], v116 offset:96
	ds_read_b64 v[102:103], v116 offset:112
	ds_read_b64 v[96:97], v116 offset:0x1100
	ds_read_b64 v[98:99], v116 offset:0x1110
	ds_read_b64 v[92:93], v116 offset:0x1120
	ds_read_b64 v[94:95], v116 offset:0x1130
	ds_read_b64 v[88:89], v116 offset:0x1140
	ds_read_b64 v[90:91], v116 offset:0x1150
	ds_read_b64 v[84:85], v116 offset:0x1160
	ds_read_b64 v[86:87], v116 offset:0x1170
	v_add_f32_e64 v68, v78, v68
	v_add_f32_e64 v69, v79, v69
	s_waitcnt lgkmcnt(0)
	v_add_f32_e32 v68, v68, v69
	v_add_f32_e32 v68, v160, v68
	v_mov_b32_e32 v69, v68
	v_mfma_f32_32x32x16_bf16 v[32:47], v[112:115], v[64:67], v[32:47]
	s_nop 0
	v_permlane32_swap_b32_e32 v68, v69
	v_add_f32_e32 v68, v68, v69
	v_div_scale_f32 v69, s[0:1], v68, v68, v218
	v_rcp_f32_e32 v78, v69
	v_mfma_f32_32x32x16_bf16 v[32:47], v[108:111], v[70:73], v[32:47]
	v_fma_f32 v79, -v69, v78, 1.0
	v_fmac_f32_e32 v78, v79, v78
	v_div_scale_f32 v79, vcc, v218, v68, v218
	v_mfma_f32_32x32x16_bf16 v[16:31], v[96:99], v[64:67], v[16:31]
	v_mfma_f32_32x32x16_bf16 v[32:47], v[104:107], v[80:83], v[32:47]
	v_mfma_f32_32x32x16_bf16 v[16:31], v[92:95], v[70:73], v[16:31]
	v_mfma_f32_32x32x16_bf16 v[32:47], v[100:103], v[74:77], v[32:47]
	v_mul_f32_e32 v100, v79, v78
	v_fma_f32 v101, -v69, v100, v79
	v_fmac_f32_e32 v100, v101, v78
	v_fma_f32 v69, -v69, v100, v79
	v_div_fmas_f32 v69, v69, v78, v100
	ds_read2st64_b32 v[78:79], v215 offset1:1
	ds_read2st64_b32 v[64:65], v215 offset0:2 offset1:3
	ds_read2st64_b32 v[66:67], v215 offset0:4 offset1:5
	ds_read2st64_b32 v[96:97], v215 offset0:6 offset1:7
	v_mfma_f32_32x32x16_bf16 v[16:31], v[88:91], v[80:83], v[16:31]
	v_div_fixup_f32 v68, v69, v68, v218
	s_waitcnt lgkmcnt(2)
	v_lshlrev_b32_e32 v102, 16, v64
	v_and_b32_e32 v103, 0xffff0000, v64
	v_lshlrev_b32_e32 v104, 16, v65
	v_and_b32_e32 v105, 0xffff0000, v65
	s_waitcnt lgkmcnt(1)
	v_lshlrev_b32_e32 v106, 16, v66
	v_and_b32_e32 v107, 0xffff0000, v66
	v_lshlrev_b32_e32 v108, 16, v67
	v_and_b32_e32 v109, 0xffff0000, v67
	ds_read2st64_b32 v[64:65], v215 offset0:8 offset1:9
	ds_read2st64_b32 v[66:67], v215 offset0:10 offset1:11
	ds_read2st64_b32 v[70:71], v215 offset0:12 offset1:13
	ds_read2st64_b32 v[72:73], v215 offset0:14 offset1:15
	v_mfma_f32_32x32x16_bf16 v[16:31], v[84:87], v[74:77], v[16:31]
	s_waitcnt lgkmcnt(4)
	v_lshlrev_b32_e32 v110, 16, v96
	s_waitcnt lgkmcnt(2)
	v_lshlrev_b32_e32 v118, 16, v66
	v_lshlrev_b32_e32 v114, 16, v64
	v_and_b32_e32 v115, 0xffff0000, v64
	v_lshlrev_b32_e32 v116, 16, v65
	v_and_b32_e32 v117, 0xffff0000, v65
	v_and_b32_e32 v119, 0xffff0000, v66
	v_lshlrev_b32_e32 v120, 16, v67
	v_and_b32_e32 v121, 0xffff0000, v67
	s_waitcnt lgkmcnt(1)
; __device__ __forceinline__ float rsq(float x) { return __builtin_amdgcn_rsqf(x); }
; template <int VAR> __device__ __forceinline__ void attn_unit_a(LAS unsigned char* lds, KP p, int l, int bh, int qb, int wv) {
;     ...
;     const float inv1 = lam / lsum;
;     float ss = 0.f;
; #pragma unroll
;     for (int t = 0; t < 4; ++t)
; #pragma unroll
;         for (int i = 0; i < 8; ++i) { const unsigned ow = o0[(t * 8 + i) * 64]; const float a = __uint_as_float(ow << 16) - O[t][2 * i] * inv1, c = __uint_as_float(ow & 0xffff0000u) - O[t][2 * i + 1] * inv1;
;             O[t][2 * i] = a; O[t][2 * i + 1] = c; ss += a * a + c * c; }
;     ss = xsum32(ss);
;     const float rs = rsq(ss * (1.f / 128.f) + EPS) * (1.f - lam_init);
;     const int row = (qb == 0 ? MX + b * CTX : b * SEQ + (qb - 1) * 256) + wid * 32 + l32;
;     if (VAR != 0 && rs != 12345.f) return;
;     bf16_t* yp = (bf16_t*)(ws + WS_Y) + (size_t)row * 2048 + h * 128 + 4 * hf;
;     const float* gs = p->g_sub + l * 128 + 4 * hf;
; #pragma unroll
;     for (int t = 0; t < 4; ++t)
; #pragma unroll
;         for (int i4 = 0; i4 < 4; ++i4) { const f32x4 g = *(const f32x4*)(gs + 32 * t + 8 * i4);
	v_lshlrev_b32_e32 v122, 16, v70
	v_and_b32_e32 v123, 0xffff0000, v70
	v_lshlrev_b32_e32 v124, 16, v71
	v_and_b32_e32 v125, 0xffff0000, v71
	s_waitcnt lgkmcnt(0)
	v_lshlrev_b32_e32 v126, 16, v72
	v_and_b32_e32 v127, 0xffff0000, v72
	v_lshlrev_b32_e32 v128, 16, v73
	ds_read2st64_b32 v[64:65], v215 offset0:16 offset1:17
	v_and_b32_e32 v129, 0xffff0000, v73
	ds_read2st64_b32 v[66:67], v215 offset0:18 offset1:19
	ds_read2st64_b32 v[70:71], v215 offset0:20 offset1:21
	ds_read2st64_b32 v[72:73], v215 offset0:22 offset1:23
	v_and_b32_e32 v111, 0xffff0000, v96
	v_lshlrev_b32_e32 v112, 16, v97
	v_and_b32_e32 v113, 0xffff0000, v97
	s_waitcnt lgkmcnt(3)
	v_lshlrev_b32_e32 v130, 16, v64
	v_and_b32_e32 v131, 0xffff0000, v64
	v_lshlrev_b32_e32 v132, 16, v65
	v_and_b32_e32 v133, 0xffff0000, v65
	s_waitcnt lgkmcnt(2)
	v_lshlrev_b32_e32 v96, 16, v66
	v_and_b32_e32 v97, 0xffff0000, v66
	v_lshlrev_b32_e32 v134, 16, v67
	v_and_b32_e32 v135, 0xffff0000, v67
	s_waitcnt lgkmcnt(0)
	v_lshlrev_b32_e32 v80, 16, v72
	v_and_b32_e32 v81, 0xffff0000, v72
	v_lshlrev_b32_e32 v86, 16, v73
	ds_read2st64_b32 v[64:65], v215 offset0:24 offset1:25
	v_and_b32_e32 v87, 0xffff0000, v73
	ds_read2st64_b32 v[66:67], v215 offset0:26 offset1:27
	ds_read2st64_b32 v[72:73], v215 offset0:28 offset1:29
	ds_read2st64_b32 v[76:77], v215 offset0:30 offset1:31
	s_load_dwordx2 s[0:1], s[6:7], 0x60
	v_lshlrev_b32_e32 v98, 16, v78
	s_waitcnt lgkmcnt(0)
	v_lshlrev_b32_e32 v84, 16, v64
	v_and_b32_e32 v85, 0xffff0000, v64
	v_lshlrev_b32_e32 v88, 16, v65
	v_and_b32_e32 v89, 0xffff0000, v65
	v_lshlrev_b32_e32 v74, 16, v66
	v_and_b32_e32 v75, 0xffff0000, v66
	v_lshlrev_b32_e32 v82, 16, v67
	v_and_b32_e32 v83, 0xffff0000, v67
	v_lshlrev_b32_e32 v65, 16, v76
	v_lshlrev_b32_e32 v64, 16, v77
	v_mov_b32_e32 v66, v30
	v_mov_b32_e32 v67, v28
	v_pk_fma_f32 v[64:65], v[66:67], v[68:69], v[64:65] op_sel_hi:[1,0,1] neg_lo:[1,0,0] neg_hi:[1,0,0]
	v_and_b32_e32 v67, 0xffff0000, v76
	v_and_b32_e32 v66, 0xffff0000, v77
	v_mov_b32_e32 v28, v31
	v_pk_fma_f32 v[66:67], v[28:29], v[68:69], v[66:67] op_sel_hi:[1,0,1] neg_lo:[1,0,0] neg_hi:[1,0,0]
	v_and_b32_e32 v99, 0xffff0000, v78
	v_pk_mul_f32 v[28:29], v[66:67], v[66:67]
	v_lshlrev_b32_e32 v100, 16, v79
	v_pk_fma_f32 v[76:77], v[64:65], v[64:65], v[28:29]
	v_and_b32_e32 v28, 31, v216
	v_lshl_or_b32 v28, s18, 11, v28
	v_or_b32_e32 v28, s19, v28
	v_lshl_add_u32 v28, v214, 5, v28
	v_ashrrev_i32_e32 v29, 31, v28
	v_lshlrev_b64 v[28:29], 12, v[28:29]
	v_and_b32_e32 v101, 0xffff0000, v79
	v_lshl_add_u64 v[78:79], s[4:5], 0, v[28:29]
	v_lshrrev_b32_e32 v28, 3, v216
	v_and_b32_e32 v136, 4, v28
	s_add_u32 s0, s0, s2
	s_addc_u32 s1, s1, s3
	v_lshlrev_b32_e32 v137, 2, v136
	global_load_dwordx4 v[28:31], v137, s[0:1]
	global_load_dwordx4 v[138:141], v137, s[0:1] offset:32
	global_load_dwordx4 v[142:145], v137, s[0:1] offset:64
	global_load_dwordx4 v[146:149], v137, s[0:1] offset:96
	global_load_dwordx4 v[150:153], v137, s[0:1] offset:128
	global_load_dwordx4 v[154:157], v137, s[0:1] offset:160
	global_load_dwordx4 v[158:161], v137, s[0:1] offset:192
	global_load_dwordx4 v[162:165], v137, s[0:1] offset:224
	global_load_dwordx4 v[166:169], v137, s[0:1] offset:256
	global_load_dwordx4 v[178:181], v137, s[0:1] offset:288
	global_load_dwordx4 v[182:185], v137, s[0:1] offset:320
	global_load_dwordx4 v[186:189], v137, s[0:1] offset:352
	global_load_dwordx4 v[204:207], v137, s[0:1] offset:384
	global_load_dwordx4 v[208:211], v137, s[0:1] offset:416
	global_load_dwordx4 v[212:215], v137, s[0:1] offset:448
	global_load_dwordx4 v[218:221], v137, s[0:1] offset:480
	v_sub_f32_e32 v69, 1.0, v217
	v_pk_fma_f32 v[2:3], v[2:3], v[68:69], v[100:101] op_sel_hi:[1,0,1] neg_lo:[1,0,0] neg_hi:[1,0,0]
	v_pk_fma_f32 v[48:49], v[48:49], v[68:69], v[114:115] op_sel_hi:[1,0,1] neg_lo:[1,0,0] neg_hi:[1,0,0]
	v_mul_f32_e32 v94, v3, v3
	v_pk_fma_f32 v[100:101], v[2:3], v[2:3], v[94:95] op_sel_hi:[1,1,0]
	v_pk_fma_f32 v[94:95], v[0:1], v[68:69], v[98:99] op_sel_hi:[1,0,1] neg_lo:[1,0,0] neg_hi:[1,0,0]
	v_pk_fma_f32 v[52:53], v[52:53], v[68:69], v[118:119] op_sel_hi:[1,0,1] neg_lo:[1,0,0] neg_hi:[1,0,0]
	v_mul_f32_e32 v0, v95, v95
	v_pk_fma_f32 v[0:1], v[94:95], v[94:95], v[0:1] op_sel_hi:[1,1,0]
	v_pk_fma_f32 v[56:57], v[56:57], v[68:69], v[122:123] op_sel_hi:[1,0,1] neg_lo:[1,0,0] neg_hi:[1,0,0]
	v_pk_add_f32 v[98:99], v[0:1], v[100:101]
	v_pk_fma_f32 v[0:1], v[6:7], v[68:69], v[104:105] op_sel_hi:[1,0,1] neg_lo:[1,0,0] neg_hi:[1,0,0]
	v_pk_fma_f32 v[60:61], v[60:61], v[68:69], v[126:127] op_sel_hi:[1,0,1] neg_lo:[1,0,0] neg_hi:[1,0,0]
	v_mul_f32_e32 v6, v1, v1
	v_pk_fma_f32 v[100:101], v[0:1], v[0:1], v[6:7] op_sel_hi:[1,1,0]
	v_pk_fma_f32 v[6:7], v[4:5], v[68:69], v[102:103] op_sel_hi:[1,0,1] neg_lo:[1,0,0] neg_hi:[1,0,0]
	v_pk_fma_f32 v[32:33], v[32:33], v[68:69], v[130:131] op_sel_hi:[1,0,1] neg_lo:[1,0,0] neg_hi:[1,0,0]
	v_mul_f32_e32 v4, v7, v7
	v_pk_fma_f32 v[4:5], v[6:7], v[6:7], v[4:5] op_sel_hi:[1,1,0]
	v_pk_fma_f32 v[34:35], v[34:35], v[68:69], v[132:133] op_sel_hi:[1,0,1] neg_lo:[1,0,0] neg_hi:[1,0,0]
	v_pk_add_f32 v[4:5], v[4:5], v[98:99]
	v_pk_fma_f32 v[36:37], v[36:37], v[68:69], v[96:97] op_sel_hi:[1,0,1] neg_lo:[1,0,0] neg_hi:[1,0,0]
	v_pk_add_f32 v[98:99], v[100:101], v[4:5]
	v_pk_fma_f32 v[4:5], v[10:11], v[68:69], v[108:109] op_sel_hi:[1,0,1] neg_lo:[1,0,0] neg_hi:[1,0,0]
	v_lshlrev_b32_e32 v90, 16, v70
	v_mul_f32_e32 v10, v5, v5
	v_pk_fma_f32 v[100:101], v[4:5], v[4:5], v[10:11] op_sel_hi:[1,1,0]
	v_pk_fma_f32 v[10:11], v[8:9], v[68:69], v[106:107] op_sel_hi:[1,0,1] neg_lo:[1,0,0] neg_hi:[1,0,0]
	v_and_b32_e32 v91, 0xffff0000, v70
	v_mul_f32_e32 v8, v11, v11
; __device__ __forceinline__ float rsq(float x) { return __builtin_amdgcn_rsqf(x); }
; template <int VAR> __device__ __forceinline__ void attn_unit_a(LAS unsigned char* lds, KP p, int l, int bh, int qb, int wv) {
;     ...
;         for (int i = 0; i < 8; ++i) { const unsigned ow = o0[(t * 8 + i) * 64]; const float a = __uint_as_float(ow << 16) - O[t][2 * i] * inv1, c = __uint_as_float(ow & 0xffff0000u) - O[t][2 * i + 1] * inv1;
;             O[t][2 * i] = a; O[t][2 * i + 1] = c; ss += a * a + c * c; }
;     ss = xsum32(ss);
;     const float rs = rsq(ss * (1.f / 128.f) + EPS) * (1.f - lam_init);
;     const int row = (qb == 0 ? MX + b * CTX : b * SEQ + (qb - 1) * 256) + wid * 32 + l32;
;     if (VAR != 0 && rs != 12345.f) return;
;     bf16_t* yp = (bf16_t*)(ws + WS_Y) + (size_t)row * 2048 + h * 128 + 4 * hf;
	v_pk_fma_f32 v[8:9], v[10:11], v[10:11], v[8:9] op_sel_hi:[1,1,0]
	v_pk_fma_f32 v[38:39], v[38:39], v[68:69], v[134:135] op_sel_hi:[1,0,1] neg_lo:[1,0,0] neg_hi:[1,0,0]
	v_pk_add_f32 v[8:9], v[8:9], v[98:99]
	v_mul_f32_e32 v96, v37, v37
	v_pk_add_f32 v[98:99], v[100:101], v[8:9]
	v_pk_fma_f32 v[100:101], v[12:13], v[68:69], v[110:111] op_sel_hi:[1,0,1] neg_lo:[1,0,0] neg_hi:[1,0,0]
	v_pk_fma_f32 v[8:9], v[14:15], v[68:69], v[112:113] op_sel_hi:[1,0,1] neg_lo:[1,0,0] neg_hi:[1,0,0]
	v_mul_f32_e32 v12, v101, v101
	v_mul_f32_e32 v14, v9, v9
	v_pk_fma_f32 v[12:13], v[100:101], v[100:101], v[12:13] op_sel_hi:[1,1,0]
	v_pk_fma_f32 v[14:15], v[8:9], v[8:9], v[14:15] op_sel_hi:[1,1,0]
	v_pk_add_f32 v[12:13], v[12:13], v[98:99]
	v_mul_f32_e32 v98, v49, v49
	v_pk_add_f32 v[14:15], v[14:15], v[12:13]
	v_pk_fma_f32 v[12:13], v[50:51], v[68:69], v[116:117] op_sel_hi:[1,0,1] neg_lo:[1,0,0] neg_hi:[1,0,0]
	v_pk_fma_f32 v[98:99], v[48:49], v[48:49], v[98:99] op_sel_hi:[1,1,0]
	v_mul_f32_e32 v50, v13, v13
	v_pk_fma_f32 v[50:51], v[12:13], v[12:13], v[50:51] op_sel_hi:[1,1,0]
	v_pk_add_f32 v[14:15], v[98:99], v[14:15]
	v_mul_f32_e32 v98, v53, v53
	v_pk_add_f32 v[14:15], v[50:51], v[14:15]
	v_pk_fma_f32 v[50:51], v[54:55], v[68:69], v[120:121] op_sel_hi:[1,0,1] neg_lo:[1,0,0] neg_hi:[1,0,0]
	v_pk_fma_f32 v[98:99], v[52:53], v[52:53], v[98:99] op_sel_hi:[1,1,0]
	v_mul_f32_e32 v54, v51, v51
	v_pk_fma_f32 v[54:55], v[50:51], v[50:51], v[54:55] op_sel_hi:[1,1,0]
	v_pk_add_f32 v[14:15], v[98:99], v[14:15]
	v_mul_f32_e32 v98, v57, v57
	v_pk_add_f32 v[14:15], v[54:55], v[14:15]
	v_pk_fma_f32 v[54:55], v[58:59], v[68:69], v[124:125] op_sel_hi:[1,0,1] neg_lo:[1,0,0] neg_hi:[1,0,0]
	v_pk_fma_f32 v[98:99], v[56:57], v[56:57], v[98:99] op_sel_hi:[1,1,0]
	v_mul_f32_e32 v58, v55, v55
	v_pk_fma_f32 v[58:59], v[54:55], v[54:55], v[58:59] op_sel_hi:[1,1,0]
	v_pk_add_f32 v[14:15], v[98:99], v[14:15]
	v_mul_f32_e32 v98, v61, v61
	v_pk_add_f32 v[14:15], v[58:59], v[14:15]
	v_pk_fma_f32 v[58:59], v[62:63], v[68:69], v[128:129] op_sel_hi:[1,0,1] neg_lo:[1,0,0] neg_hi:[1,0,0]
	v_pk_fma_f32 v[98:99], v[60:61], v[60:61], v[98:99] op_sel_hi:[1,1,0]
	v_mul_f32_e32 v62, v59, v59
	v_pk_fma_f32 v[62:63], v[58:59], v[58:59], v[62:63] op_sel_hi:[1,1,0]
	v_pk_add_f32 v[14:15], v[98:99], v[14:15]
	v_mul_f32_e32 v98, v33, v33
	v_pk_add_f32 v[14:15], v[62:63], v[14:15]
	v_mul_f32_e32 v62, v35, v35
	v_pk_fma_f32 v[98:99], v[32:33], v[32:33], v[98:99] op_sel_hi:[1,1,0]
	v_pk_fma_f32 v[62:63], v[34:35], v[34:35], v[62:63] op_sel_hi:[1,1,0]
	v_pk_add_f32 v[14:15], v[98:99], v[14:15]
	v_lshlrev_b32_e32 v92, 16, v71
	v_and_b32_e32 v93, 0xffff0000, v71
	v_pk_add_f32 v[14:15], v[62:63], v[14:15]
	v_mul_f32_e32 v62, v39, v39
	v_pk_fma_f32 v[96:97], v[36:37], v[36:37], v[96:97] op_sel_hi:[1,1,0]
	v_pk_fma_f32 v[40:41], v[40:41], v[68:69], v[90:91] op_sel_hi:[1,0,1] neg_lo:[1,0,0] neg_hi:[1,0,0]
	v_pk_fma_f32 v[62:63], v[38:39], v[38:39], v[62:63] op_sel_hi:[1,1,0]
	v_pk_add_f32 v[14:15], v[96:97], v[14:15]
	v_pk_fma_f32 v[42:43], v[42:43], v[68:69], v[92:93] op_sel_hi:[1,0,1] neg_lo:[1,0,0] neg_hi:[1,0,0]
	v_mul_f32_e32 v90, v41, v41
	v_pk_add_f32 v[14:15], v[62:63], v[14:15]
	v_mul_f32_e32 v62, v43, v43
	v_pk_fma_f32 v[90:91], v[40:41], v[40:41], v[90:91] op_sel_hi:[1,1,0]
	v_pk_fma_f32 v[44:45], v[44:45], v[68:69], v[80:81] op_sel_hi:[1,0,1] neg_lo:[1,0,0] neg_hi:[1,0,0]
	v_pk_fma_f32 v[62:63], v[42:43], v[42:43], v[62:63] op_sel_hi:[1,1,0]
	v_pk_add_f32 v[14:15], v[90:91], v[14:15]
	v_mul_f32_e32 v80, v45, v45
	v_pk_add_f32 v[14:15], v[62:63], v[14:15]
	v_pk_fma_f32 v[46:47], v[46:47], v[68:69], v[86:87] op_sel_hi:[1,0,1] neg_lo:[1,0,0] neg_hi:[1,0,0]
	v_pk_fma_f32 v[80:81], v[44:45], v[44:45], v[80:81] op_sel_hi:[1,1,0]
	v_mul_f32_e32 v62, v47, v47
	v_pk_add_f32 v[14:15], v[80:81], v[14:15]
	v_pk_fma_f32 v[80:81], v[16:17], v[68:69], v[84:85] op_sel_hi:[1,0,1] neg_lo:[1,0,0] neg_hi:[1,0,0]
	v_pk_fma_f32 v[62:63], v[46:47], v[46:47], v[62:63] op_sel_hi:[1,1,0]
	v_pk_fma_f32 v[18:19], v[18:19], v[68:69], v[88:89] op_sel_hi:[1,0,1] neg_lo:[1,0,0] neg_hi:[1,0,0]
	v_mul_f32_e32 v16, v81, v81
	v_pk_add_f32 v[14:15], v[62:63], v[14:15]
	v_mul_f32_e32 v62, v19, v19
	v_pk_fma_f32 v[16:17], v[80:81], v[80:81], v[16:17] op_sel_hi:[1,1,0]
	v_pk_fma_f32 v[62:63], v[18:19], v[18:19], v[62:63] op_sel_hi:[1,1,0]
	v_pk_add_f32 v[14:15], v[16:17], v[14:15]
	v_pk_fma_f32 v[20:21], v[20:21], v[68:69], v[74:75] op_sel_hi:[1,0,1] neg_lo:[1,0,0] neg_hi:[1,0,0]
	v_lshlrev_b32_e32 v70, 16, v72
	v_and_b32_e32 v71, 0xffff0000, v72
	v_pk_add_f32 v[14:15], v[62:63], v[14:15]
	v_pk_fma_f32 v[22:23], v[22:23], v[68:69], v[82:83] op_sel_hi:[1,0,1] neg_lo:[1,0,0] neg_hi:[1,0,0]
	v_mul_f32_e32 v62, v21, v21
	v_lshlrev_b32_e32 v72, 16, v73
	v_and_b32_e32 v73, 0xffff0000, v73
	v_mul_f32_e32 v16, v23, v23
	v_pk_fma_f32 v[62:63], v[20:21], v[20:21], v[62:63] op_sel_hi:[1,1,0]
	v_pk_fma_f32 v[24:25], v[24:25], v[68:69], v[70:71] op_sel_hi:[1,0,1] neg_lo:[1,0,0] neg_hi:[1,0,0]
	v_pk_fma_f32 v[16:17], v[22:23], v[22:23], v[16:17] op_sel_hi:[1,1,0]
	v_pk_add_f32 v[14:15], v[62:63], v[14:15]
	v_pk_fma_f32 v[26:27], v[26:27], v[68:69], v[72:73] op_sel_hi:[1,0,1] neg_lo:[1,0,0] neg_hi:[1,0,0]
	v_mul_f32_e32 v62, v25, v25
	v_pk_add_f32 v[14:15], v[16:17], v[14:15]
	v_mul_f32_e32 v16, v27, v27
	v_pk_fma_f32 v[62:63], v[24:25], v[24:25], v[62:63] op_sel_hi:[1,1,0]
	v_pk_fma_f32 v[16:17], v[26:27], v[26:27], v[16:17] op_sel_hi:[1,1,0]
	v_pk_add_f32 v[14:15], v[62:63], v[14:15]
	v_lshlrev_b32_e32 v192, 1, v136
	v_pk_add_f32 v[14:15], v[16:17], v[14:15]
	s_mov_b32 s2, 0x3c00000
	v_pk_add_f32 v[14:15], v[76:77], v[14:15] op_sel:[1,0] op_sel_hi:[0,1]
	v_pk_add_f32 v[14:15], v[76:77], v[14:15]
	s_nop 0
	v_mov_b32_e32 v15, v14
	s_nop 1
	v_permlane32_swap_b32_e32 v14, v15
	v_add_f32_e32 v14, v14, v15
	v_fmamk_f32 v14, v14, 0x3c000000, v225
	v_rsq_f32_e32 v16, v14
	v_lshl_add_u64 v[14:15], v[78:79], 0, s[76:77]
	v_lshl_add_u64 v[62:63], v[14:15], 0, v[192:193]
	v_mul_f32_e32 v68, v69, v16
	v_pk_mul_f32 v[14:15], v[94:95], v[68:69] op_sel_hi:[1,0]
	v_pk_mul_f32 v[2:3], v[2:3], v[68:69] op_sel_hi:[1,0]
	s_waitcnt vmcnt(0)
; __device__ __forceinline__ u32x2 pack4(f32x4 v) { u32x2 w; w.x = cvtpk(v[0], v[1]); w.y = cvtpk(v[2], v[3]); return w; }
; template <int VAR> __device__ __forceinline__ void attn_unit_a(LAS unsigned char* lds, KP p, int l, int bh, int qb, int wv) {
;     ...
; #pragma unroll
;     for (int t = 0; t < 4; ++t)
; #pragma unroll
;         for (int i4 = 0; i4 < 4; ++i4) { const f32x4 g = *(const f32x4*)(gs + 32 * t + 8 * i4);
;             f32x4 v; v[0] = O[t][4 * i4] * rs * g[0]; v[1] = O[t][4 * i4 + 1] * rs * g[1]; v[2] = O[t][4 * i4 + 2] * rs * g[2]; v[3] = O[t][4 * i4 + 3] * rs * g[3];
;             *(u32x2*)(yp + 32 * t + 8 * i4) = pack4(v); }
	v_pk_mul_f32 v[14:15], v[28:29], v[14:15]
	v_pk_mul_f32 v[2:3], v[30:31], v[2:3]
	v_cvt_pk_bf16_f32 v14, v14, v15
	v_cvt_pk_bf16_f32 v15, v2, v3
	v_add_co_u32_e32 v2, vcc, s2, v62
	v_pk_mul_f32 v[0:1], v[0:1], v[68:69] op_sel_hi:[1,0]
	s_nop 0
	v_addc_co_u32_e32 v3, vcc, 0, v63, vcc
	global_store_dwordx2 v[2:3], v[14:15], off
	v_pk_mul_f32 v[2:3], v[6:7], v[68:69] op_sel_hi:[1,0]
	s_mov_b64 s[2:3], 0x3c00000
	v_lshl_add_u64 v[28:29], v[62:63], 0, s[2:3]
	v_pk_mul_f32 v[6:7], v[10:11], v[68:69] op_sel_hi:[1,0]
	v_pk_mul_f32 v[4:5], v[4:5], v[68:69] op_sel_hi:[1,0]
	v_pk_mul_f32 v[2:3], v[138:139], v[2:3]
	v_pk_mul_f32 v[0:1], v[140:141], v[0:1]
	v_cvt_pk_bf16_f32 v2, v2, v3
	v_cvt_pk_bf16_f32 v3, v0, v1
	global_store_dwordx2 v[28:29], v[2:3], off offset:16
	v_pk_mul_f32 v[0:1], v[142:143], v[6:7]
	v_pk_mul_f32 v[2:3], v[144:145], v[4:5]
	v_cvt_pk_bf16_f32 v0, v0, v1
	v_cvt_pk_bf16_f32 v1, v2, v3
	global_store_dwordx2 v[28:29], v[0:1], off offset:32
	v_pk_mul_f32 v[4:5], v[100:101], v[68:69] op_sel_hi:[1,0]
	v_pk_mul_f32 v[6:7], v[12:13], v[68:69] op_sel_hi:[1,0]
	v_pk_mul_f32 v[0:1], v[4:5], v[146:147]
	v_pk_mul_f32 v[4:5], v[8:9], v[68:69] op_sel_hi:[1,0]
	v_cvt_pk_bf16_f32 v0, v0, v1
	v_pk_mul_f32 v[2:3], v[4:5], v[148:149]
	v_pk_mul_f32 v[4:5], v[48:49], v[68:69] op_sel_hi:[1,0]
	v_cvt_pk_bf16_f32 v1, v2, v3
	global_store_dwordx2 v[28:29], v[0:1], off offset:48
	v_pk_mul_f32 v[0:1], v[4:5], v[150:151]
	v_pk_mul_f32 v[2:3], v[6:7], v[152:153]
	v_cvt_pk_bf16_f32 v0, v0, v1
	v_cvt_pk_bf16_f32 v1, v2, v3
	global_store_dwordx2 v[28:29], v[0:1], off offset:64
	v_pk_mul_f32 v[4:5], v[52:53], v[68:69] op_sel_hi:[1,0]
	v_pk_mul_f32 v[6:7], v[50:51], v[68:69] op_sel_hi:[1,0]
	v_pk_mul_f32 v[0:1], v[4:5], v[154:155]
	v_pk_mul_f32 v[2:3], v[6:7], v[156:157]
	v_cvt_pk_bf16_f32 v0, v0, v1
	v_cvt_pk_bf16_f32 v1, v2, v3
	global_store_dwordx2 v[28:29], v[0:1], off offset:80
	v_pk_mul_f32 v[4:5], v[56:57], v[68:69] op_sel_hi:[1,0]
	v_pk_mul_f32 v[6:7], v[54:55], v[68:69] op_sel_hi:[1,0]
	v_pk_mul_f32 v[0:1], v[4:5], v[158:159]
	v_pk_mul_f32 v[2:3], v[6:7], v[160:161]
	v_cvt_pk_bf16_f32 v0, v0, v1
	v_cvt_pk_bf16_f32 v1, v2, v3
	global_store_dwordx2 v[28:29], v[0:1], off offset:96
	v_pk_mul_f32 v[4:5], v[60:61], v[68:69] op_sel_hi:[1,0]
	v_pk_mul_f32 v[6:7], v[58:59], v[68:69] op_sel_hi:[1,0]
	v_pk_mul_f32 v[0:1], v[4:5], v[162:163]
	v_pk_mul_f32 v[2:3], v[6:7], v[164:165]
	v_cvt_pk_bf16_f32 v0, v0, v1
	v_cvt_pk_bf16_f32 v1, v2, v3
	global_store_dwordx2 v[28:29], v[0:1], off offset:112
	v_pk_mul_f32 v[4:5], v[32:33], v[68:69] op_sel_hi:[1,0]
	v_pk_mul_f32 v[6:7], v[34:35], v[68:69] op_sel_hi:[1,0]
	v_pk_mul_f32 v[0:1], v[4:5], v[166:167]
	v_pk_mul_f32 v[2:3], v[6:7], v[168:169]
	v_cvt_pk_bf16_f32 v0, v0, v1
	v_cvt_pk_bf16_f32 v1, v2, v3
	global_store_dwordx2 v[28:29], v[0:1], off offset:128
	v_pk_mul_f32 v[4:5], v[36:37], v[68:69] op_sel_hi:[1,0]
	v_pk_mul_f32 v[6:7], v[38:39], v[68:69] op_sel_hi:[1,0]
	v_pk_mul_f32 v[0:1], v[4:5], v[178:179]
	v_pk_mul_f32 v[2:3], v[6:7], v[180:181]
	v_cvt_pk_bf16_f32 v0, v0, v1
	v_cvt_pk_bf16_f32 v1, v2, v3
	global_store_dwordx2 v[28:29], v[0:1], off offset:144
	v_pk_mul_f32 v[4:5], v[40:41], v[68:69] op_sel_hi:[1,0]
	v_pk_mul_f32 v[6:7], v[42:43], v[68:69] op_sel_hi:[1,0]
	v_pk_mul_f32 v[0:1], v[4:5], v[182:183]
	v_pk_mul_f32 v[2:3], v[6:7], v[184:185]
	v_cvt_pk_bf16_f32 v0, v0, v1
	v_cvt_pk_bf16_f32 v1, v2, v3
	global_store_dwordx2 v[28:29], v[0:1], off offset:160
	v_pk_mul_f32 v[4:5], v[44:45], v[68:69] op_sel_hi:[1,0]
	v_pk_mul_f32 v[6:7], v[46:47], v[68:69] op_sel_hi:[1,0]
	v_pk_mul_f32 v[0:1], v[4:5], v[186:187]
	v_pk_mul_f32 v[2:3], v[6:7], v[188:189]
	v_cvt_pk_bf16_f32 v0, v0, v1
	v_cvt_pk_bf16_f32 v1, v2, v3
	global_store_dwordx2 v[28:29], v[0:1], off offset:176
	v_pk_mul_f32 v[4:5], v[80:81], v[68:69] op_sel_hi:[1,0]
	v_pk_mul_f32 v[6:7], v[18:19], v[68:69] op_sel_hi:[1,0]
	v_pk_mul_f32 v[0:1], v[4:5], v[204:205]
	v_pk_mul_f32 v[2:3], v[6:7], v[206:207]
	v_cvt_pk_bf16_f32 v0, v0, v1
	v_cvt_pk_bf16_f32 v1, v2, v3
	global_store_dwordx2 v[28:29], v[0:1], off offset:192
	v_pk_mul_f32 v[4:5], v[20:21], v[68:69] op_sel_hi:[1,0]
	v_pk_mul_f32 v[6:7], v[22:23], v[68:69] op_sel_hi:[1,0]
	v_pk_mul_f32 v[0:1], v[4:5], v[208:209]
	v_pk_mul_f32 v[2:3], v[6:7], v[210:211]
	v_cvt_pk_bf16_f32 v0, v0, v1
	v_cvt_pk_bf16_f32 v1, v2, v3
	global_store_dwordx2 v[28:29], v[0:1], off offset:208
	v_pk_mul_f32 v[4:5], v[24:25], v[68:69] op_sel_hi:[1,0]
	v_pk_mul_f32 v[6:7], v[26:27], v[68:69] op_sel_hi:[1,0]
	v_pk_mul_f32 v[0:1], v[4:5], v[212:213]
	v_pk_mul_f32 v[2:3], v[6:7], v[214:215]
	v_cvt_pk_bf16_f32 v0, v0, v1
	v_cvt_pk_bf16_f32 v1, v2, v3
	global_store_dwordx2 v[28:29], v[0:1], off offset:224
	v_mov_b32_e32 v4, v65
	v_mov_b32_e32 v5, v67
	v_mov_b32_e32 v65, v66
	v_pk_mul_f32 v[4:5], v[4:5], v[68:69] op_sel_hi:[1,0]
	v_pk_mul_f32 v[6:7], v[64:65], v[68:69] op_sel_hi:[1,0]
	v_pk_mul_f32 v[0:1], v[4:5], v[218:219]
	v_pk_mul_f32 v[2:3], v[6:7], v[220:221]
	v_cvt_pk_bf16_f32 v0, v0, v1
	v_cvt_pk_bf16_f32 v1, v2, v3
	global_store_dwordx2 v[28:29], v[0:1], off offset:240

; template <int VAR> __device__ __forceinline__ void attn_unit_a(LAS unsigned char* lds, KP p, int l, int bh, int qb, int wv) {
;     ...
;     const float inv1 = lam / lsum;
;     float ss = 0.f;
; #pragma unroll
;     for (int t = 0; t < 4; ++t)
; #pragma unroll
;         for (int i = 0; i < 8; ++i) { const unsigned ow = o0[(t * 8 + i) * 64]; const float a = __uint_as_float(ow << 16) - O[t][2 * i] * inv1, c = __uint_as_float(ow & 0xffff0000u) - O[t][2 * i + 1] * inv1;
.LBB0_911:
	v_exp_f32_e32 v130, v80
	v_exp_f32_e32 v131, v81
	v_exp_f32_e32 v134, v82
	v_exp_f32_e32 v135, v83
	v_exp_f32_e32 v84, v84
	v_exp_f32_e32 v85, v85
	v_exp_f32_e32 v86, v86
	v_exp_f32_e32 v87, v87
	v_exp_f32_e32 v132, v64
	v_exp_f32_e32 v133, v65
	v_exp_f32_e32 v136, v66
	v_exp_f32_e32 v137, v67
	v_cvt_pk_bf16_f32 v64, v130, v131
	v_cvt_pk_bf16_f32 v65, v134, v135
	v_cvt_pk_bf16_f32 v66, v84, v85
	v_cvt_pk_bf16_f32 v67, v86, v87
	s_waitcnt lgkmcnt(0)
	v_exp_f32_e32 v88, v88
	v_exp_f32_e32 v89, v89
	v_mfma_f32_32x32x16_bf16 v[48:63], v[124:127], v[64:67], v[48:63]
	v_exp_f32_e32 v142, v90
	v_exp_f32_e32 v143, v91
	v_exp_f32_e32 v144, v92
	v_exp_f32_e32 v145, v93
	v_exp_f32_e32 v124, v94
	v_exp_f32_e32 v125, v95
	v_exp_f32_e32 v138, v70
	v_mfma_f32_32x32x16_bf16 v[32:47], v[108:111], v[64:67], v[32:47]
	v_exp_f32_e32 v139, v71
	v_exp_f32_e32 v140, v72
	v_exp_f32_e32 v141, v73
	v_cvt_pk_bf16_f32 v70, v88, v89
	v_cvt_pk_bf16_f32 v71, v142, v143
	v_cvt_pk_bf16_f32 v72, v144, v145
	v_cvt_pk_bf16_f32 v73, v124, v125
	v_exp_f32_e32 v68, v68
	v_exp_f32_e32 v69, v69
	v_mfma_f32_32x32x16_bf16 v[48:63], v[120:123], v[70:73], v[48:63]
	v_cvt_pk_bf16_f32 v80, v132, v133
	v_cvt_pk_bf16_f32 v81, v136, v137
	v_cvt_pk_bf16_f32 v82, v68, v69
	v_cvt_pk_bf16_f32 v83, v138, v139
	v_add_f32_e64 v90, v130, 0
	v_add_f32_e64 v91, v131, 0
	v_exp_f32_e32 v120, v74
	v_pk_add_f32 v[90:91], v[132:133], v[90:91]
	v_mfma_f32_32x32x16_bf16 v[32:47], v[104:107], v[70:73], v[32:47]
	v_add_f32_e64 v90, v134, v90
	v_add_f32_e64 v91, v135, v91
	v_exp_f32_e32 v121, v75
	v_exp_f32_e32 v122, v76
	v_exp_f32_e32 v123, v77
	v_exp_f32_e32 v78, v78
	v_exp_f32_e32 v79, v79
	v_pk_add_f32 v[90:91], v[136:137], v[90:91]
	v_mfma_f32_32x32x16_bf16 v[48:63], v[116:119], v[80:83], v[48:63]
	v_add_f32_e64 v84, v84, v90
	v_add_f32_e64 v85, v85, v91
	v_cvt_pk_bf16_f32 v74, v140, v141
	v_add_f32_e64 v68, v68, v84
	v_add_f32_e64 v69, v69, v85
	v_cvt_pk_bf16_f32 v75, v120, v121
	v_pk_add_f32 v[68:69], v[86:87], v[68:69]
	v_cvt_pk_bf16_f32 v76, v122, v123
	v_cvt_pk_bf16_f32 v77, v78, v79
	v_mfma_f32_32x32x16_bf16 v[32:47], v[100:103], v[80:83], v[32:47]
	v_add_f32_e64 v68, v138, v68
	v_add_f32_e64 v69, v139, v69
	v_readlane_b32 s2, v255, 45
	v_add_f32_e64 v68, v88, v68
	v_add_f32_e64 v69, v89, v69
	v_readlane_b32 s3, v255, 46
	v_pk_add_f32 v[68:69], v[140:141], v[68:69]
	s_lshl_b32 s76, s10, 8
	v_pk_add_f32 v[68:69], v[142:143], v[68:69]
	v_mfma_f32_32x32x16_bf16 v[48:63], v[112:115], v[74:77], v[48:63]
	v_add_f32_e64 v68, v120, v68
	v_add_f32_e64 v69, v121, v69
	s_lshl_b64 s[2:3], s[2:3], 2
	v_add_f32_e64 v68, v144, v68
	v_add_f32_e64 v69, v145, v69
	v_pk_add_f32 v[68:69], v[122:123], v[68:69]
	s_nop 0
	v_pk_add_f32 v[68:69], v[124:125], v[68:69]
	v_mfma_f32_32x32x16_bf16 v[32:47], v[96:99], v[74:77], v[32:47]
	ds_read_b64 v[112:113], v187
	ds_read_b64 v[114:115], v187 offset:16
	ds_read_b64 v[108:109], v187 offset:32
	ds_read_b64 v[110:111], v187 offset:48
	ds_read_b64 v[104:105], v187 offset:64
	ds_read_b64 v[106:107], v187 offset:80
	ds_read_b64 v[100:101], v187 offset:96
	ds_read_b64 v[102:103], v187 offset:112
	ds_read_b64 v[96:97], v187 offset:0x1100
	ds_read_b64 v[98:99], v187 offset:0x1110
	ds_read_b64 v[92:93], v187 offset:0x1120
	ds_read_b64 v[94:95], v187 offset:0x1130
	ds_read_b64 v[88:89], v187 offset:0x1140
	ds_read_b64 v[90:91], v187 offset:0x1150
	ds_read_b64 v[84:85], v187 offset:0x1160
	ds_read_b64 v[86:87], v187 offset:0x1170
	v_add_f32_e64 v68, v78, v68
	v_add_f32_e64 v69, v79, v69
	s_waitcnt lgkmcnt(0)
	v_add_f32_e32 v68, v68, v69
	v_add_f32_e32 v68, v128, v68
	v_mov_b32_e32 v69, v68
	v_mfma_f32_32x32x16_bf16 v[16:31], v[112:115], v[64:67], v[16:31]
	s_nop 0
	v_permlane32_swap_b32_e32 v68, v69
	v_add_f32_e32 v68, v68, v69
	v_div_scale_f32 v69, s[0:1], v68, v68, v182
	v_rcp_f32_e32 v78, v69
	s_lshl_b32 s0, s11, 8
	v_mfma_f32_32x32x16_bf16 v[16:31], v[108:111], v[70:73], v[16:31]
	s_addk_i32 s0, 0x4000
	v_fma_f32 v79, -v69, v78, 1.0
	v_fmac_f32_e32 v78, v79, v78
	v_div_scale_f32 v79, vcc, v182, v68, v182
	v_mfma_f32_32x32x16_bf16 v[0:15], v[96:99], v[64:67], v[0:15]
	v_mfma_f32_32x32x16_bf16 v[16:31], v[104:107], v[80:83], v[16:31]
	v_mul_f32_e32 v104, v79, v78
	v_mfma_f32_32x32x16_bf16 v[0:15], v[92:95], v[70:73], v[0:15]
	v_mfma_f32_32x32x16_bf16 v[16:31], v[100:103], v[74:77], v[16:31]
	v_fma_f32 v100, -v69, v104, v79
	v_fmac_f32_e32 v104, v100, v78
	v_fma_f32 v69, -v69, v104, v79
	v_div_fmas_f32 v69, v69, v78, v104
	ds_read2st64_b32 v[78:79], v184 offset1:1
	ds_read2st64_b32 v[64:65], v184 offset0:2 offset1:3
	ds_read2st64_b32 v[66:67], v184 offset0:4 offset1:5
	ds_read2st64_b32 v[96:97], v184 offset0:6 offset1:7
	v_div_fixup_f32 v68, v69, v68, v182
	v_mfma_f32_32x32x16_bf16 v[0:15], v[88:91], v[80:83], v[0:15]
	s_waitcnt lgkmcnt(2)
	v_lshlrev_b32_e32 v102, 16, v64
	v_and_b32_e32 v103, 0xffff0000, v64
	v_lshlrev_b32_e32 v104, 16, v65
	v_and_b32_e32 v105, 0xffff0000, v65
	s_waitcnt lgkmcnt(1)
	v_lshlrev_b32_e32 v106, 16, v66
	v_and_b32_e32 v107, 0xffff0000, v66
	v_lshlrev_b32_e32 v108, 16, v67
	v_and_b32_e32 v109, 0xffff0000, v67
	ds_read2st64_b32 v[64:65], v184 offset0:8 offset1:9
	ds_read2st64_b32 v[66:67], v184 offset0:10 offset1:11
	ds_read2st64_b32 v[70:71], v184 offset0:12 offset1:13
	ds_read2st64_b32 v[72:73], v184 offset0:14 offset1:15
	v_mfma_f32_32x32x16_bf16 v[0:15], v[84:87], v[74:77], v[0:15]
	s_waitcnt lgkmcnt(3)
	v_lshlrev_b32_e32 v114, 16, v64
	v_and_b32_e32 v115, 0xffff0000, v64
	v_lshlrev_b32_e32 v116, 16, v65
	v_and_b32_e32 v117, 0xffff0000, v65
	s_waitcnt lgkmcnt(2)
; __device__ __forceinline__ float rsq(float x) { return __builtin_amdgcn_rsqf(x); }
; template <int VAR> __device__ __forceinline__ void attn_unit_a(LAS unsigned char* lds, KP p, int l, int bh, int qb, int wv) {
;     ...
;     const float inv1 = lam / lsum;
;     float ss = 0.f;
; #pragma unroll
;     for (int t = 0; t < 4; ++t)
; #pragma unroll
;         for (int i = 0; i < 8; ++i) { const unsigned ow = o0[(t * 8 + i) * 64]; const float a = __uint_as_float(ow << 16) - O[t][2 * i] * inv1, c = __uint_as_float(ow & 0xffff0000u) - O[t][2 * i + 1] * inv1;
;             O[t][2 * i] = a; O[t][2 * i + 1] = c; ss += a * a + c * c; }
;     ss = xsum32(ss);
;     const float rs = rsq(ss * (1.f / 128.f) + EPS) * (1.f - lam_init);
;     const int row = (qb == 0 ? MX + b * CTX : b * SEQ + (qb - 1) * 256) + wid * 32 + l32;
;     if (VAR != 0 && rs != 12345.f) return;
;     bf16_t* yp = (bf16_t*)(ws + WS_Y) + (size_t)row * 2048 + h * 128 + 4 * hf;
;     const float* gs = p->g_sub + l * 128 + 4 * hf;
; #pragma unroll
;     for (int t = 0; t < 4; ++t)
; #pragma unroll
;         for (int i4 = 0; i4 < 4; ++i4) { const f32x4 g = *(const f32x4*)(gs + 32 * t + 8 * i4);
	v_lshlrev_b32_e32 v118, 16, v66
	v_and_b32_e32 v119, 0xffff0000, v66
	v_lshlrev_b32_e32 v120, 16, v67
	v_and_b32_e32 v121, 0xffff0000, v67
	s_waitcnt lgkmcnt(1)
	v_lshlrev_b32_e32 v122, 16, v70
	v_and_b32_e32 v123, 0xffff0000, v70
	v_lshlrev_b32_e32 v124, 16, v71
	v_and_b32_e32 v125, 0xffff0000, v71
	s_waitcnt lgkmcnt(0)
	v_lshlrev_b32_e32 v126, 16, v72
	v_and_b32_e32 v127, 0xffff0000, v72
	v_lshlrev_b32_e32 v128, 16, v73
	ds_read2st64_b32 v[64:65], v184 offset0:16 offset1:17
	v_and_b32_e32 v129, 0xffff0000, v73
	ds_read2st64_b32 v[66:67], v184 offset0:18 offset1:19
	ds_read2st64_b32 v[70:71], v184 offset0:20 offset1:21
	ds_read2st64_b32 v[72:73], v184 offset0:22 offset1:23
	v_lshlrev_b32_e32 v110, 16, v96
	v_and_b32_e32 v111, 0xffff0000, v96
	v_lshlrev_b32_e32 v112, 16, v97
	v_and_b32_e32 v113, 0xffff0000, v97
	s_waitcnt lgkmcnt(3)
	v_lshlrev_b32_e32 v130, 16, v64
	v_and_b32_e32 v131, 0xffff0000, v64
	v_lshlrev_b32_e32 v132, 16, v65
	v_and_b32_e32 v133, 0xffff0000, v65
	s_waitcnt lgkmcnt(2)
	v_lshlrev_b32_e32 v96, 16, v66
	v_and_b32_e32 v97, 0xffff0000, v66
	v_lshlrev_b32_e32 v134, 16, v67
	v_and_b32_e32 v135, 0xffff0000, v67
	s_waitcnt lgkmcnt(0)
	v_lshlrev_b32_e32 v80, 16, v72
	v_and_b32_e32 v81, 0xffff0000, v72
	v_lshlrev_b32_e32 v86, 16, v73
	ds_read2st64_b32 v[64:65], v184 offset0:24 offset1:25
	v_and_b32_e32 v87, 0xffff0000, v73
	ds_read2st64_b32 v[66:67], v184 offset0:26 offset1:27
	ds_read2st64_b32 v[72:73], v184 offset0:28 offset1:29
	ds_read2st64_b32 v[76:77], v184 offset0:30 offset1:31
	v_lshlrev_b32_e32 v98, 16, v78
	v_and_b32_e32 v99, 0xffff0000, v78
	s_waitcnt lgkmcnt(3)
	v_lshlrev_b32_e32 v84, 16, v64
	v_and_b32_e32 v85, 0xffff0000, v64
	v_lshlrev_b32_e32 v88, 16, v65
	v_and_b32_e32 v89, 0xffff0000, v65
	s_waitcnt lgkmcnt(2)
	v_lshlrev_b32_e32 v74, 16, v66
	v_and_b32_e32 v75, 0xffff0000, v66
	v_lshlrev_b32_e32 v82, 16, v67
	v_and_b32_e32 v83, 0xffff0000, v67
	s_waitcnt lgkmcnt(0)
	v_lshlrev_b32_e32 v65, 16, v76
	v_lshlrev_b32_e32 v64, 16, v77
	v_mov_b32_e32 v66, v14
	v_mov_b32_e32 v67, v12
	v_pk_fma_f32 v[64:65], v[66:67], v[68:69], v[64:65] op_sel_hi:[1,0,1] neg_lo:[1,0,0] neg_hi:[1,0,0]
	v_and_b32_e32 v67, 0xffff0000, v76
	v_and_b32_e32 v66, 0xffff0000, v77
	v_mov_b32_e32 v12, v15
	v_pk_fma_f32 v[66:67], v[12:13], v[68:69], v[66:67] op_sel_hi:[1,0,1] neg_lo:[1,0,0] neg_hi:[1,0,0]
	v_lshlrev_b32_e32 v100, 16, v79
	v_pk_mul_f32 v[12:13], v[66:67], v[66:67]
	v_and_b32_e32 v101, 0xffff0000, v79
	v_pk_fma_f32 v[76:77], v[64:65], v[64:65], v[12:13]
	v_and_or_b32 v12, v180, 31, s0
	s_load_dwordx2 s[0:1], s[6:7], 0x60
	v_lshl_add_u32 v12, v183, 5, v12
	v_ashrrev_i32_e32 v13, 31, v12
	v_lshlrev_b64 v[12:13], 12, v[12:13]
	v_lshl_add_u64 v[78:79], s[8:9], 0, v[12:13]
	v_lshrrev_b32_e32 v12, 3, v180
	v_and_b32_e32 v136, 4, v12
	s_waitcnt lgkmcnt(0)
	s_add_u32 s0, s0, s2
	s_addc_u32 s1, s1, s3
	v_lshlrev_b32_e32 v137, 2, v136
	global_load_dwordx4 v[12:15], v137, s[0:1]
	global_load_dwordx4 v[138:141], v137, s[0:1] offset:32
	global_load_dwordx4 v[142:145], v137, s[0:1] offset:64
	global_load_dwordx4 v[146:149], v137, s[0:1] offset:96
	global_load_dwordx4 v[150:153], v137, s[0:1] offset:128
	global_load_dwordx4 v[154:157], v137, s[0:1] offset:160
	global_load_dwordx4 v[158:161], v137, s[0:1] offset:192
	global_load_dwordx4 v[162:165], v137, s[0:1] offset:224
	global_load_dwordx4 v[166:169], v137, s[0:1] offset:256
	global_load_dwordx4 v[182:185], v137, s[0:1] offset:288
	global_load_dwordx4 v[186:189], v137, s[0:1] offset:320
	global_load_dwordx4 v[204:207], v137, s[0:1] offset:352
	global_load_dwordx4 v[208:211], v137, s[0:1] offset:384
	global_load_dwordx4 v[212:215], v137, s[0:1] offset:416
	global_load_dwordx4 v[216:219], v137, s[0:1] offset:448
	global_load_dwordx4 v[220:223], v137, s[0:1] offset:480
	v_sub_f32_e32 v69, 1.0, v181
	v_pk_fma_f32 v[50:51], v[50:51], v[68:69], v[100:101] op_sel_hi:[1,0,1] neg_lo:[1,0,0] neg_hi:[1,0,0]
	v_pk_fma_f32 v[60:61], v[60:61], v[68:69], v[110:111] op_sel_hi:[1,0,1] neg_lo:[1,0,0] neg_hi:[1,0,0]
	v_mul_f32_e32 v94, v51, v51
	v_pk_fma_f32 v[100:101], v[50:51], v[50:51], v[94:95] op_sel_hi:[1,1,0]
	v_pk_fma_f32 v[94:95], v[48:49], v[68:69], v[98:99] op_sel_hi:[1,0,1] neg_lo:[1,0,0] neg_hi:[1,0,0]
	v_pk_fma_f32 v[32:33], v[32:33], v[68:69], v[114:115] op_sel_hi:[1,0,1] neg_lo:[1,0,0] neg_hi:[1,0,0]
	v_mul_f32_e32 v48, v95, v95
	v_pk_fma_f32 v[48:49], v[94:95], v[94:95], v[48:49] op_sel_hi:[1,1,0]
	v_pk_fma_f32 v[34:35], v[34:35], v[68:69], v[116:117] op_sel_hi:[1,0,1] neg_lo:[1,0,0] neg_hi:[1,0,0]
	v_pk_add_f32 v[98:99], v[48:49], v[100:101]
	v_pk_fma_f32 v[48:49], v[54:55], v[68:69], v[104:105] op_sel_hi:[1,0,1] neg_lo:[1,0,0] neg_hi:[1,0,0]
	v_pk_fma_f32 v[36:37], v[36:37], v[68:69], v[118:119] op_sel_hi:[1,0,1] neg_lo:[1,0,0] neg_hi:[1,0,0]
	v_mul_f32_e32 v54, v49, v49
	v_pk_fma_f32 v[100:101], v[48:49], v[48:49], v[54:55] op_sel_hi:[1,1,0]
	v_pk_fma_f32 v[54:55], v[52:53], v[68:69], v[102:103] op_sel_hi:[1,0,1] neg_lo:[1,0,0] neg_hi:[1,0,0]
	v_pk_fma_f32 v[38:39], v[38:39], v[68:69], v[120:121] op_sel_hi:[1,0,1] neg_lo:[1,0,0] neg_hi:[1,0,0]
	v_mul_f32_e32 v52, v55, v55
	v_pk_fma_f32 v[52:53], v[54:55], v[54:55], v[52:53] op_sel_hi:[1,1,0]
	v_pk_fma_f32 v[40:41], v[40:41], v[68:69], v[122:123] op_sel_hi:[1,0,1] neg_lo:[1,0,0] neg_hi:[1,0,0]
	v_pk_add_f32 v[52:53], v[52:53], v[98:99]
	v_pk_fma_f32 v[42:43], v[42:43], v[68:69], v[124:125] op_sel_hi:[1,0,1] neg_lo:[1,0,0] neg_hi:[1,0,0]
	v_pk_add_f32 v[98:99], v[100:101], v[52:53]
	v_pk_fma_f32 v[52:53], v[58:59], v[68:69], v[108:109] op_sel_hi:[1,0,1] neg_lo:[1,0,0] neg_hi:[1,0,0]
	v_pk_fma_f32 v[44:45], v[44:45], v[68:69], v[126:127] op_sel_hi:[1,0,1] neg_lo:[1,0,0] neg_hi:[1,0,0]
; __device__ __forceinline__ float rsq(float x) { return __builtin_amdgcn_rsqf(x); }
; template <int VAR> __device__ __forceinline__ void attn_unit_a(LAS unsigned char* lds, KP p, int l, int bh, int qb, int wv) {
;     ...
;         for (int i = 0; i < 8; ++i) { const unsigned ow = o0[(t * 8 + i) * 64]; const float a = __uint_as_float(ow << 16) - O[t][2 * i] * inv1, c = __uint_as_float(ow & 0xffff0000u) - O[t][2 * i + 1] * inv1;
;             O[t][2 * i] = a; O[t][2 * i + 1] = c; ss += a * a + c * c; }
;     ss = xsum32(ss);
;     const float rs = rsq(ss * (1.f / 128.f) + EPS) * (1.f - lam_init);
;     const int row = (qb == 0 ? MX + b * CTX : b * SEQ + (qb - 1) * 256) + wid * 32 + l32;
;     if (VAR != 0 && rs != 12345.f) return;
;     bf16_t* yp = (bf16_t*)(ws + WS_Y) + (size_t)row * 2048 + h * 128 + 4 * hf;
	v_mul_f32_e32 v58, v53, v53
	v_pk_fma_f32 v[100:101], v[52:53], v[52:53], v[58:59] op_sel_hi:[1,1,0]
	v_pk_fma_f32 v[58:59], v[56:57], v[68:69], v[106:107] op_sel_hi:[1,0,1] neg_lo:[1,0,0] neg_hi:[1,0,0]
	v_pk_fma_f32 v[46:47], v[46:47], v[68:69], v[128:129] op_sel_hi:[1,0,1] neg_lo:[1,0,0] neg_hi:[1,0,0]
	v_mul_f32_e32 v56, v59, v59
	v_pk_fma_f32 v[56:57], v[58:59], v[58:59], v[56:57] op_sel_hi:[1,1,0]
	v_pk_fma_f32 v[16:17], v[16:17], v[68:69], v[130:131] op_sel_hi:[1,0,1] neg_lo:[1,0,0] neg_hi:[1,0,0]
	v_pk_add_f32 v[56:57], v[56:57], v[98:99]
	v_pk_fma_f32 v[18:19], v[18:19], v[68:69], v[132:133] op_sel_hi:[1,0,1] neg_lo:[1,0,0] neg_hi:[1,0,0]
	v_pk_add_f32 v[98:99], v[100:101], v[56:57]
	v_pk_fma_f32 v[56:57], v[62:63], v[68:69], v[112:113] op_sel_hi:[1,0,1] neg_lo:[1,0,0] neg_hi:[1,0,0]
	v_mul_f32_e32 v100, v61, v61
	v_mul_f32_e32 v62, v57, v57
	v_pk_fma_f32 v[100:101], v[60:61], v[60:61], v[100:101] op_sel_hi:[1,1,0]
	v_pk_fma_f32 v[62:63], v[56:57], v[56:57], v[62:63] op_sel_hi:[1,1,0]
	v_pk_add_f32 v[98:99], v[100:101], v[98:99]
	v_mul_f32_e32 v100, v33, v33
	v_pk_add_f32 v[62:63], v[62:63], v[98:99]
	v_mul_f32_e32 v98, v35, v35
	v_pk_fma_f32 v[100:101], v[32:33], v[32:33], v[100:101] op_sel_hi:[1,1,0]
	v_pk_fma_f32 v[98:99], v[34:35], v[34:35], v[98:99] op_sel_hi:[1,1,0]
	v_pk_add_f32 v[62:63], v[100:101], v[62:63]
	v_mul_f32_e32 v100, v37, v37
	v_pk_add_f32 v[62:63], v[98:99], v[62:63]
	v_mul_f32_e32 v98, v39, v39
	v_pk_fma_f32 v[100:101], v[36:37], v[36:37], v[100:101] op_sel_hi:[1,1,0]
	v_pk_fma_f32 v[98:99], v[38:39], v[38:39], v[98:99] op_sel_hi:[1,1,0]
	v_pk_add_f32 v[62:63], v[100:101], v[62:63]
	v_mul_f32_e32 v100, v41, v41
	v_pk_add_f32 v[62:63], v[98:99], v[62:63]
	v_mul_f32_e32 v98, v43, v43
	v_pk_fma_f32 v[100:101], v[40:41], v[40:41], v[100:101] op_sel_hi:[1,1,0]
	v_pk_fma_f32 v[98:99], v[42:43], v[42:43], v[98:99] op_sel_hi:[1,1,0]
	v_pk_add_f32 v[62:63], v[100:101], v[62:63]
	v_mul_f32_e32 v100, v45, v45
	v_pk_add_f32 v[62:63], v[98:99], v[62:63]
	v_mul_f32_e32 v98, v47, v47
	v_pk_fma_f32 v[100:101], v[44:45], v[44:45], v[100:101] op_sel_hi:[1,1,0]
	v_pk_fma_f32 v[98:99], v[46:47], v[46:47], v[98:99] op_sel_hi:[1,1,0]
	v_pk_add_f32 v[62:63], v[100:101], v[62:63]
	v_mul_f32_e32 v100, v17, v17
	v_pk_add_f32 v[62:63], v[98:99], v[62:63]
	v_mul_f32_e32 v98, v19, v19
	v_pk_fma_f32 v[100:101], v[16:17], v[16:17], v[100:101] op_sel_hi:[1,1,0]
	v_pk_fma_f32 v[20:21], v[20:21], v[68:69], v[96:97] op_sel_hi:[1,0,1] neg_lo:[1,0,0] neg_hi:[1,0,0]
	v_lshlrev_b32_e32 v90, 16, v70
	v_and_b32_e32 v91, 0xffff0000, v70
	v_pk_fma_f32 v[98:99], v[18:19], v[18:19], v[98:99] op_sel_hi:[1,1,0]
	v_pk_add_f32 v[62:63], v[100:101], v[62:63]
	v_pk_fma_f32 v[22:23], v[22:23], v[68:69], v[134:135] op_sel_hi:[1,0,1] neg_lo:[1,0,0] neg_hi:[1,0,0]
	v_mul_f32_e32 v96, v21, v21
	v_lshlrev_b32_e32 v92, 16, v71
	v_and_b32_e32 v93, 0xffff0000, v71
	v_pk_add_f32 v[62:63], v[98:99], v[62:63]
	v_mul_f32_e32 v98, v23, v23
	v_pk_fma_f32 v[96:97], v[20:21], v[20:21], v[96:97] op_sel_hi:[1,1,0]
	v_pk_fma_f32 v[24:25], v[24:25], v[68:69], v[90:91] op_sel_hi:[1,0,1] neg_lo:[1,0,0] neg_hi:[1,0,0]
	v_pk_fma_f32 v[98:99], v[22:23], v[22:23], v[98:99] op_sel_hi:[1,1,0]
	v_pk_add_f32 v[62:63], v[96:97], v[62:63]
	v_pk_fma_f32 v[26:27], v[26:27], v[68:69], v[92:93] op_sel_hi:[1,0,1] neg_lo:[1,0,0] neg_hi:[1,0,0]
	v_mul_f32_e32 v90, v25, v25
	v_pk_add_f32 v[62:63], v[98:99], v[62:63]
	v_mul_f32_e32 v92, v27, v27
	v_pk_fma_f32 v[90:91], v[24:25], v[24:25], v[90:91] op_sel_hi:[1,1,0]
	v_pk_fma_f32 v[28:29], v[28:29], v[68:69], v[80:81] op_sel_hi:[1,0,1] neg_lo:[1,0,0] neg_hi:[1,0,0]
	v_pk_fma_f32 v[92:93], v[26:27], v[26:27], v[92:93] op_sel_hi:[1,1,0]
	v_pk_add_f32 v[62:63], v[90:91], v[62:63]
	v_pk_fma_f32 v[30:31], v[30:31], v[68:69], v[86:87] op_sel_hi:[1,0,1] neg_lo:[1,0,0] neg_hi:[1,0,0]
	v_mul_f32_e32 v80, v29, v29
	v_pk_add_f32 v[62:63], v[92:93], v[62:63]
	v_mul_f32_e32 v86, v31, v31
	v_pk_fma_f32 v[80:81], v[28:29], v[28:29], v[80:81] op_sel_hi:[1,1,0]
	v_pk_fma_f32 v[84:85], v[0:1], v[68:69], v[84:85] op_sel_hi:[1,0,1] neg_lo:[1,0,0] neg_hi:[1,0,0]
	v_pk_fma_f32 v[86:87], v[30:31], v[30:31], v[86:87] op_sel_hi:[1,1,0]
	v_pk_add_f32 v[62:63], v[80:81], v[62:63]
	v_pk_fma_f32 v[80:81], v[2:3], v[68:69], v[88:89] op_sel_hi:[1,0,1] neg_lo:[1,0,0] neg_hi:[1,0,0]
	v_mul_f32_e32 v0, v85, v85
	v_pk_add_f32 v[62:63], v[86:87], v[62:63]
	v_mul_f32_e32 v2, v81, v81
	v_pk_fma_f32 v[0:1], v[84:85], v[84:85], v[0:1] op_sel_hi:[1,1,0]
	v_pk_fma_f32 v[4:5], v[4:5], v[68:69], v[74:75] op_sel_hi:[1,0,1] neg_lo:[1,0,0] neg_hi:[1,0,0]
	v_lshlrev_b32_e32 v70, 16, v72
	v_and_b32_e32 v71, 0xffff0000, v72
	v_pk_fma_f32 v[2:3], v[80:81], v[80:81], v[2:3] op_sel_hi:[1,1,0]
	v_pk_add_f32 v[0:1], v[0:1], v[62:63]
	v_pk_fma_f32 v[6:7], v[6:7], v[68:69], v[82:83] op_sel_hi:[1,0,1] neg_lo:[1,0,0] neg_hi:[1,0,0]
	v_mul_f32_e32 v62, v5, v5
	v_lshlrev_b32_e32 v72, 16, v73
	v_and_b32_e32 v73, 0xffff0000, v73
	v_pk_add_f32 v[0:1], v[2:3], v[0:1]
	v_mul_f32_e32 v2, v7, v7
	v_pk_fma_f32 v[62:63], v[4:5], v[4:5], v[62:63] op_sel_hi:[1,1,0]
	v_pk_fma_f32 v[8:9], v[8:9], v[68:69], v[70:71] op_sel_hi:[1,0,1] neg_lo:[1,0,0] neg_hi:[1,0,0]
	v_pk_fma_f32 v[2:3], v[6:7], v[6:7], v[2:3] op_sel_hi:[1,1,0]
	v_pk_add_f32 v[0:1], v[62:63], v[0:1]
	v_pk_fma_f32 v[10:11], v[10:11], v[68:69], v[72:73] op_sel_hi:[1,0,1] neg_lo:[1,0,0] neg_hi:[1,0,0]
	v_mul_f32_e32 v62, v9, v9
	v_pk_add_f32 v[0:1], v[2:3], v[0:1]
	v_mul_f32_e32 v2, v11, v11
	v_pk_fma_f32 v[62:63], v[8:9], v[8:9], v[62:63] op_sel_hi:[1,1,0]
	v_pk_fma_f32 v[2:3], v[10:11], v[10:11], v[2:3] op_sel_hi:[1,1,0]
	v_pk_add_f32 v[0:1], v[62:63], v[0:1]
	v_lshlrev_b32_e32 v192, 1, v136
	v_pk_add_f32 v[0:1], v[2:3], v[0:1]
	s_mov_b32 s2, 0x3c00000
	v_pk_add_f32 v[0:1], v[76:77], v[0:1] op_sel:[1,0] op_sel_hi:[0,1]
	v_pk_add_f32 v[0:1], v[76:77], v[0:1]
	s_nop 0
	v_mov_b32_e32 v1, v0
	s_nop 1
	v_permlane32_swap_b32_e32 v0, v1
	v_add_f32_e32 v0, v0, v1
	v_fmamk_f32 v0, v0, 0x3c000000, v225
	v_rsq_f32_e32 v2, v0
	v_lshl_add_u64 v[0:1], v[78:79], 0, s[76:77]
	v_lshl_add_u64 v[62:63], v[0:1], 0, v[192:193]
	v_mul_f32_e32 v68, v69, v2
	v_pk_mul_f32 v[0:1], v[94:95], v[68:69] op_sel_hi:[1,0]
	v_pk_mul_f32 v[2:3], v[50:51], v[68:69] op_sel_hi:[1,0]
	s_waitcnt vmcnt(0)
; __device__ __forceinline__ u32x2 pack4(f32x4 v) { u32x2 w; w.x = cvtpk(v[0], v[1]); w.y = cvtpk(v[2], v[3]); return w; }
; template <int VAR> __device__ __forceinline__ void attn_unit_a(LAS unsigned char* lds, KP p, int l, int bh, int qb, int wv) {
;     ...
; #pragma unroll
;     for (int t = 0; t < 4; ++t)
; #pragma unroll
;         for (int i4 = 0; i4 < 4; ++i4) { const f32x4 g = *(const f32x4*)(gs + 32 * t + 8 * i4);
;             f32x4 v; v[0] = O[t][4 * i4] * rs * g[0]; v[1] = O[t][4 * i4 + 1] * rs * g[1]; v[2] = O[t][4 * i4 + 2] * rs * g[2]; v[3] = O[t][4 * i4 + 3] * rs * g[3];
;             *(u32x2*)(yp + 32 * t + 8 * i4) = pack4(v); }
	v_pk_mul_f32 v[0:1], v[12:13], v[0:1]
	v_pk_mul_f32 v[2:3], v[14:15], v[2:3]
	v_cvt_pk_bf16_f32 v0, v0, v1
	v_cvt_pk_bf16_f32 v1, v2, v3
	v_add_co_u32_e32 v2, vcc, s2, v62
	v_pk_mul_f32 v[14:15], v[54:55], v[68:69] op_sel_hi:[1,0]
	s_nop 0
	v_addc_co_u32_e32 v3, vcc, 0, v63, vcc
	global_store_dwordx2 v[2:3], v[0:1], off
	s_mov_b64 s[2:3], 0x3c00000
	v_lshl_add_u64 v[12:13], v[62:63], 0, s[2:3]
	v_pk_mul_f32 v[4:5], v[4:5], v[68:69] op_sel_hi:[1,0]
	v_pk_mul_f32 v[6:7], v[6:7], v[68:69] op_sel_hi:[1,0]
	v_pk_mul_f32 v[0:1], v[138:139], v[14:15]
	v_pk_mul_f32 v[14:15], v[48:49], v[68:69] op_sel_hi:[1,0]
	v_cvt_pk_bf16_f32 v0, v0, v1
	v_pk_mul_f32 v[2:3], v[140:141], v[14:15]
	v_pk_mul_f32 v[14:15], v[58:59], v[68:69] op_sel_hi:[1,0]
	v_cvt_pk_bf16_f32 v1, v2, v3
	global_store_dwordx2 v[12:13], v[0:1], off offset:16
	v_pk_mul_f32 v[0:1], v[142:143], v[14:15]
	v_pk_mul_f32 v[14:15], v[52:53], v[68:69] op_sel_hi:[1,0]
	v_cvt_pk_bf16_f32 v0, v0, v1
	v_pk_mul_f32 v[2:3], v[144:145], v[14:15]
	v_pk_mul_f32 v[14:15], v[60:61], v[68:69] op_sel_hi:[1,0]
	v_cvt_pk_bf16_f32 v1, v2, v3
	global_store_dwordx2 v[12:13], v[0:1], off offset:32
	v_pk_mul_f32 v[0:1], v[14:15], v[146:147]
	v_pk_mul_f32 v[14:15], v[56:57], v[68:69] op_sel_hi:[1,0]
	v_cvt_pk_bf16_f32 v0, v0, v1
	v_pk_mul_f32 v[2:3], v[14:15], v[148:149]
	v_pk_mul_f32 v[14:15], v[32:33], v[68:69] op_sel_hi:[1,0]
	v_cvt_pk_bf16_f32 v1, v2, v3
	global_store_dwordx2 v[12:13], v[0:1], off offset:48
	v_pk_mul_f32 v[32:33], v[34:35], v[68:69] op_sel_hi:[1,0]
	v_pk_mul_f32 v[0:1], v[14:15], v[150:151]
	v_pk_mul_f32 v[2:3], v[32:33], v[152:153]
	v_cvt_pk_bf16_f32 v0, v0, v1
	v_cvt_pk_bf16_f32 v1, v2, v3
	global_store_dwordx2 v[12:13], v[0:1], off offset:64
	v_pk_mul_f32 v[14:15], v[36:37], v[68:69] op_sel_hi:[1,0]
	v_pk_mul_f32 v[32:33], v[38:39], v[68:69] op_sel_hi:[1,0]
	v_pk_mul_f32 v[0:1], v[14:15], v[154:155]
	v_pk_mul_f32 v[2:3], v[32:33], v[156:157]
	v_cvt_pk_bf16_f32 v0, v0, v1
	v_cvt_pk_bf16_f32 v1, v2, v3
	global_store_dwordx2 v[12:13], v[0:1], off offset:80
	v_pk_mul_f32 v[14:15], v[40:41], v[68:69] op_sel_hi:[1,0]
	v_pk_mul_f32 v[32:33], v[42:43], v[68:69] op_sel_hi:[1,0]
	v_pk_mul_f32 v[0:1], v[14:15], v[158:159]
	v_pk_mul_f32 v[2:3], v[32:33], v[160:161]
	v_cvt_pk_bf16_f32 v0, v0, v1
	v_cvt_pk_bf16_f32 v1, v2, v3
	global_store_dwordx2 v[12:13], v[0:1], off offset:96
	v_pk_mul_f32 v[14:15], v[44:45], v[68:69] op_sel_hi:[1,0]
	v_pk_mul_f32 v[32:33], v[46:47], v[68:69] op_sel_hi:[1,0]
	v_pk_mul_f32 v[0:1], v[14:15], v[162:163]
	v_pk_mul_f32 v[2:3], v[32:33], v[164:165]
	v_cvt_pk_bf16_f32 v0, v0, v1
	v_cvt_pk_bf16_f32 v1, v2, v3
	global_store_dwordx2 v[12:13], v[0:1], off offset:112
	v_pk_mul_f32 v[14:15], v[16:17], v[68:69] op_sel_hi:[1,0]
	v_pk_mul_f32 v[16:17], v[18:19], v[68:69] op_sel_hi:[1,0]
	v_pk_mul_f32 v[0:1], v[14:15], v[166:167]
	v_pk_mul_f32 v[2:3], v[16:17], v[168:169]
	v_cvt_pk_bf16_f32 v0, v0, v1
	v_cvt_pk_bf16_f32 v1, v2, v3
	global_store_dwordx2 v[12:13], v[0:1], off offset:128
	v_pk_mul_f32 v[14:15], v[20:21], v[68:69] op_sel_hi:[1,0]
	v_pk_mul_f32 v[16:17], v[22:23], v[68:69] op_sel_hi:[1,0]
	v_pk_mul_f32 v[0:1], v[14:15], v[182:183]
	v_pk_mul_f32 v[2:3], v[16:17], v[184:185]
	v_cvt_pk_bf16_f32 v0, v0, v1
	v_cvt_pk_bf16_f32 v1, v2, v3
	global_store_dwordx2 v[12:13], v[0:1], off offset:144
	v_pk_mul_f32 v[14:15], v[24:25], v[68:69] op_sel_hi:[1,0]
	v_pk_mul_f32 v[16:17], v[26:27], v[68:69] op_sel_hi:[1,0]
	v_pk_mul_f32 v[0:1], v[14:15], v[186:187]
	v_pk_mul_f32 v[2:3], v[16:17], v[188:189]
	v_cvt_pk_bf16_f32 v0, v0, v1
	v_cvt_pk_bf16_f32 v1, v2, v3
	global_store_dwordx2 v[12:13], v[0:1], off offset:160
	v_pk_mul_f32 v[14:15], v[28:29], v[68:69] op_sel_hi:[1,0]
	v_pk_mul_f32 v[16:17], v[30:31], v[68:69] op_sel_hi:[1,0]
	v_pk_mul_f32 v[0:1], v[14:15], v[204:205]
	v_pk_mul_f32 v[2:3], v[16:17], v[206:207]
	v_cvt_pk_bf16_f32 v0, v0, v1
	v_cvt_pk_bf16_f32 v1, v2, v3
	global_store_dwordx2 v[12:13], v[0:1], off offset:176
	v_pk_mul_f32 v[14:15], v[84:85], v[68:69] op_sel_hi:[1,0]
	v_pk_mul_f32 v[16:17], v[80:81], v[68:69] op_sel_hi:[1,0]
	v_pk_mul_f32 v[0:1], v[14:15], v[208:209]
	v_pk_mul_f32 v[2:3], v[16:17], v[210:211]
	v_cvt_pk_bf16_f32 v0, v0, v1
	v_cvt_pk_bf16_f32 v1, v2, v3
	global_store_dwordx2 v[12:13], v[0:1], off offset:192
	v_pk_mul_f32 v[0:1], v[4:5], v[212:213]
	v_pk_mul_f32 v[2:3], v[6:7], v[214:215]
	v_cvt_pk_bf16_f32 v0, v0, v1
	v_cvt_pk_bf16_f32 v1, v2, v3
	global_store_dwordx2 v[12:13], v[0:1], off offset:208
	v_pk_mul_f32 v[4:5], v[8:9], v[68:69] op_sel_hi:[1,0]
	v_pk_mul_f32 v[6:7], v[10:11], v[68:69] op_sel_hi:[1,0]
	v_pk_mul_f32 v[0:1], v[4:5], v[216:217]
	v_pk_mul_f32 v[2:3], v[6:7], v[218:219]
	v_cvt_pk_bf16_f32 v0, v0, v1
	v_cvt_pk_bf16_f32 v1, v2, v3
	global_store_dwordx2 v[12:13], v[0:1], off offset:224
	v_mov_b32_e32 v4, v65
	v_mov_b32_e32 v5, v67
	v_mov_b32_e32 v65, v66
	v_pk_mul_f32 v[4:5], v[4:5], v[68:69] op_sel_hi:[1,0]
	v_pk_mul_f32 v[6:7], v[64:65], v[68:69] op_sel_hi:[1,0]
	s_mov_b64 s[0:1], 0
	v_pk_mul_f32 v[0:1], v[4:5], v[220:221]
	v_pk_mul_f32 v[2:3], v[6:7], v[222:223]
	v_cvt_pk_bf16_f32 v0, v0, v1
	v_cvt_pk_bf16_f32 v1, v2, v3
	global_store_dwordx2 v[12:13], v[0:1], off offset:240
